# v25 + combine row loop: lines of the row after next touched by 12 dword loads (L2 warm-up), counted waits leave them outstanding
# baseline (speedup 1.0000x reference)
.LBB0_326:
	s_or_b64 exec, exec, s[8:9]
	v_lshlrev_b32_e32 v74, 16, v64
	v_and_b32_e32 v75, 0xffff0000, v64
	v_lshlrev_b32_e32 v76, 16, v66
	v_and_b32_e32 v77, 0xffff0000, v66
	v_lshlrev_b32_e32 v64, 16, v65
	v_and_b32_e32 v65, 0xffff0000, v65
	v_lshlrev_b32_e32 v66, 16, v67
	v_and_b32_e32 v67, 0xffff0000, v67
	v_pk_add_f32 v[74:75], v[76:77], v[74:75]
	v_pk_add_f32 v[64:65], v[66:67], v[64:65]
	v_mov_b32_e32 v76, v75
	v_mov_b32_e32 v77, v65
	v_mov_b32_e32 v66, v74
	v_mov_b32_e32 v67, v64
	v_pk_mul_f32 v[76:77], v[76:77], v[76:77]
	s_mov_b32 s0, 0x3e85000
	v_pk_fma_f32 v[66:67], v[66:67], v[66:67], v[76:77]
	s_nop 0
	v_add_f32_e32 v66, v66, v67
	s_nop 1
	v_add_f32_dpp v66, v66, v66 quad_perm:[1,0,3,2] row_mask:0xf bank_mask:0xf bound_ctrl:1
	s_nop 1
	v_add_f32_dpp v66, v66, v66 quad_perm:[2,3,0,1] row_mask:0xf bank_mask:0xf bound_ctrl:1
	s_nop 1
	v_add_f32_dpp v66, v66, v66 row_half_mirror row_mask:0xf bank_mask:0xf bound_ctrl:1
	s_nop 1
	v_add_f32_dpp v66, v66, v66 row_mirror row_mask:0xf bank_mask:0xf bound_ctrl:1
	v_fmamk_f32 v66, v66, 0x3c800000, v237
	v_rsq_f32_e32 v66, v66
	s_nop 0
	v_pk_mul_f32 v[74:75], v[74:75], v[66:67] op_sel_hi:[1,0]
	v_pk_mul_f32 v[64:65], v[64:65], v[66:67] op_sel_hi:[1,0]
	v_pk_mul_f32 v[66:67], v[4:5], v[74:75]
	v_lshlrev_b32_e32 v74, 16, v62
	v_and_b32_e32 v75, 0xffff0000, v62
	v_mul_f32_e32 v62, 0xbfb8aa3b, v74
	v_exp_f32_e32 v62, v62
	v_pk_mul_f32 v[64:65], v[6:7], v[64:65]
	v_add_f32_e32 v62, 1.0, v62
	v_rcp_f32_e32 v76, v62
	v_mul_f32_e32 v62, 0xbfb8aa3b, v75
	v_exp_f32_e32 v62, v62
	s_nop 0
	v_add_f32_e32 v62, 1.0, v62
	v_rcp_f32_e32 v77, v62
	v_lshlrev_b32_e32 v62, 16, v63
	v_and_b32_e32 v63, 0xffff0000, v63
	v_pk_mul_f32 v[74:75], v[76:77], v[74:75]
	s_nop 0
	v_pk_mul_f32 v[66:67], v[74:75], v[66:67]
	s_nop 0
	v_cvt_pk_bf16_f32 v66, v66, v67
	v_mul_f32_e32 v67, 0xbfb8aa3b, v62
	v_exp_f32_e32 v67, v67
	s_nop 0
	v_add_f32_e32 v67, 1.0, v67
	v_rcp_f32_e32 v74, v67
	v_mul_f32_e32 v67, 0xbfb8aa3b, v63
	v_exp_f32_e32 v67, v67
	s_nop 0
	v_add_f32_e32 v67, 1.0, v67
	v_rcp_f32_e32 v75, v67
	s_nop 0
	v_pk_mul_f32 v[62:63], v[74:75], v[62:63]
	s_nop 0
	v_pk_mul_f32 v[62:63], v[62:63], v[64:65]
	v_lshlrev_b32_e32 v64, 16, v60
	v_cvt_pk_bf16_f32 v67, v62, v63
	v_add_co_u32_e32 v62, vcc, s0, v70
	v_and_b32_e32 v65, 0xffff0000, v60
	s_nop 0
	v_addc_co_u32_e32 v63, vcc, 0, v71, vcc
	global_store_dwordx2 v[62:63], v[66:67], off
	v_lshlrev_b32_e32 v66, 16, v58
	v_and_b32_e32 v67, 0xffff0000, v58
	v_lshlrev_b32_e32 v60, 16, v61
	v_and_b32_e32 v61, 0xffff0000, v61
	v_lshlrev_b32_e32 v58, 16, v59
	v_and_b32_e32 v59, 0xffff0000, v59
	v_pk_add_f32 v[64:65], v[66:67], v[64:65]
	v_pk_add_f32 v[58:59], v[58:59], v[60:61]
	v_mov_b32_e32 v66, v65
	v_mov_b32_e32 v67, v59
	v_mov_b32_e32 v60, v64
	v_mov_b32_e32 v61, v58
	v_pk_mul_f32 v[66:67], v[66:67], v[66:67]
	s_mov_b64 s[0:1], 0x800
	v_pk_fma_f32 v[60:61], v[60:61], v[60:61], v[66:67]
	v_lshl_add_u64 v[20:21], v[20:21], 0, s[0:1]
	v_add_f32_e32 v60, v60, v61
	s_mov_b64 s[0:1], 0x1c00
	v_lshl_add_u64 v[24:25], v[24:25], 0, s[0:1]
	v_add_f32_dpp v60, v60, v60 quad_perm:[1,0,3,2] row_mask:0xf bank_mask:0xf bound_ctrl:1
	s_nop 1
	v_add_f32_dpp v60, v60, v60 quad_perm:[2,3,0,1] row_mask:0xf bank_mask:0xf bound_ctrl:1
	s_nop 1
	v_add_f32_dpp v60, v60, v60 row_half_mirror row_mask:0xf bank_mask:0xf bound_ctrl:1
	s_nop 1
	v_add_f32_dpp v60, v60, v60 row_mirror row_mask:0xf bank_mask:0xf bound_ctrl:1
	v_fmamk_f32 v60, v60, 0x3c800000, v237
	v_rsq_f32_e32 v60, v60
	s_nop 0
	v_pk_mul_f32 v[58:59], v[58:59], v[60:61] op_sel_hi:[1,0]
	v_pk_mul_f32 v[60:61], v[64:65], v[60:61] op_sel_hi:[1,0]
	v_lshlrev_b32_e32 v64, 16, v56
	v_and_b32_e32 v65, 0xffff0000, v56
	v_mul_f32_e32 v56, 0xbfb8aa3b, v64
	v_exp_f32_e32 v56, v56
	s_nop 0
	v_add_f32_e32 v56, 1.0, v56
	v_rcp_f32_e32 v66, v56
	v_mul_f32_e32 v56, 0xbfb8aa3b, v65
	v_exp_f32_e32 v56, v56
	s_nop 0
	v_add_f32_e32 v56, 1.0, v56
	v_rcp_f32_e32 v67, v56
	s_nop 0
	v_pk_mul_f32 v[64:65], v[66:67], v[64:65]
	s_nop 0
	v_pk_mul_f32 v[60:61], v[64:65], v[60:61]
	s_waitcnt vmcnt(20)
	v_mov_b64_e32 v[66:67], v[26:27]
	v_cvt_pk_bf16_f32 v56, v60, v61
	v_lshlrev_b32_e32 v60, 16, v57
	v_and_b32_e32 v61, 0xffff0000, v57
	v_mul_f32_e32 v57, 0xbfb8aa3b, v60
	v_exp_f32_e32 v57, v57
	s_nop 0
	v_add_f32_e32 v57, 1.0, v57
	v_rcp_f32_e32 v64, v57
	v_mul_f32_e32 v57, 0xbfb8aa3b, v61
	v_exp_f32_e32 v57, v57
	s_nop 0
	v_add_f32_e32 v57, 1.0, v57
	v_rcp_f32_e32 v65, v57
	s_nop 0
	v_pk_mul_f32 v[60:61], v[64:65], v[60:61]
	s_nop 0
	v_pk_mul_f32 v[58:59], v[60:61], v[58:59]
	v_mov_b64_e32 v[64:65], v[32:33]
	v_cvt_pk_bf16_f32 v57, v58, v59
	global_store_dwordx2 v[62:63], v[56:57], off offset:512
	v_lshlrev_b32_e32 v56, 16, v54
	v_and_b32_e32 v57, 0xffff0000, v54
	v_lshlrev_b32_e32 v58, 16, v52
	v_and_b32_e32 v59, 0xffff0000, v52
	v_lshlrev_b32_e32 v54, 16, v55
	v_and_b32_e32 v55, 0xffff0000, v55
	v_lshlrev_b32_e32 v52, 16, v53
	v_and_b32_e32 v53, 0xffff0000, v53
	v_pk_add_f32 v[56:57], v[58:59], v[56:57]
	v_pk_add_f32 v[52:53], v[52:53], v[54:55]
	v_mov_b32_e32 v58, v57
	v_mov_b32_e32 v59, v53
	v_mov_b32_e32 v54, v56
	v_mov_b32_e32 v55, v52
	v_pk_mul_f32 v[58:59], v[58:59], v[58:59]
	v_mov_b64_e32 v[60:61], v[38:39]
	v_pk_fma_f32 v[54:55], v[54:55], v[54:55], v[58:59]
	s_nop 0
	v_add_f32_e32 v54, v54, v55
	s_nop 1
	v_add_f32_dpp v54, v54, v54 quad_perm:[1,0,3,2] row_mask:0xf bank_mask:0xf bound_ctrl:1
	s_nop 1
	v_add_f32_dpp v54, v54, v54 quad_perm:[2,3,0,1] row_mask:0xf bank_mask:0xf bound_ctrl:1
	s_nop 1
	v_add_f32_dpp v54, v54, v54 row_half_mirror row_mask:0xf bank_mask:0xf bound_ctrl:1
	s_nop 1
	v_add_f32_dpp v54, v54, v54 row_mirror row_mask:0xf bank_mask:0xf bound_ctrl:1
	v_fmamk_f32 v54, v54, 0x3c800000, v237
	v_rsq_f32_e32 v54, v54
	s_nop 0
	v_pk_mul_f32 v[56:57], v[56:57], v[54:55] op_sel_hi:[1,0]
	v_pk_mul_f32 v[52:53], v[52:53], v[54:55] op_sel_hi:[1,0]
	v_pk_mul_f32 v[54:55], v[8:9], v[56:57]
	v_lshlrev_b32_e32 v56, 16, v50
	v_and_b32_e32 v57, 0xffff0000, v50
	v_mul_f32_e32 v50, 0xbfb8aa3b, v56
	v_exp_f32_e32 v50, v50
	v_pk_mul_f32 v[52:53], v[10:11], v[52:53]
	v_add_f32_e32 v50, 1.0, v50
	v_rcp_f32_e32 v58, v50
	v_mul_f32_e32 v50, 0xbfb8aa3b, v57
	v_exp_f32_e32 v50, v50
	s_nop 0
	v_add_f32_e32 v50, 1.0, v50
	v_rcp_f32_e32 v59, v50
	s_nop 0
	v_pk_mul_f32 v[56:57], v[58:59], v[56:57]
	s_nop 0
	v_pk_mul_f32 v[54:55], v[56:57], v[54:55]
	s_waitcnt vmcnt(20)
	v_mov_b64_e32 v[58:59], v[40:41]
	v_cvt_pk_bf16_f32 v50, v54, v55
	v_lshlrev_b32_e32 v54, 16, v51
	v_and_b32_e32 v55, 0xffff0000, v51
	v_mul_f32_e32 v51, 0xbfb8aa3b, v54
	v_exp_f32_e32 v51, v51
	s_nop 0
	v_add_f32_e32 v51, 1.0, v51
	v_rcp_f32_e32 v56, v51
	v_mul_f32_e32 v51, 0xbfb8aa3b, v55
	v_exp_f32_e32 v51, v51
	s_nop 0
	v_add_f32_e32 v51, 1.0, v51
	v_rcp_f32_e32 v57, v51
	s_nop 0
	v_pk_mul_f32 v[54:55], v[56:57], v[54:55]
	s_nop 0
	v_pk_mul_f32 v[52:53], v[54:55], v[52:53]
	s_waitcnt vmcnt(16)
	v_mov_b64_e32 v[56:57], v[30:31]
	v_cvt_pk_bf16_f32 v51, v52, v53
	global_store_dwordx2 v[62:63], v[50:51], off offset:1024
	v_lshlrev_b32_e32 v50, 16, v18
	v_and_b32_e32 v51, 0xffff0000, v18
	v_lshlrev_b32_e32 v52, 16, v16
	v_and_b32_e32 v53, 0xffff0000, v16
	v_pk_add_f32 v[50:51], v[52:53], v[50:51]
	v_lshlrev_b32_e32 v52, 16, v22
	v_and_b32_e32 v53, 0xffff0000, v22
	v_pk_fma_f32 v[50:51], v[12:13], v[52:53], v[50:51]
	v_lshlrev_b32_e32 v18, 16, v19
	v_mul_f32_e32 v16, 0x3d372713, v50
	v_mul_f32_e32 v16, v50, v16
	v_fma_f32 v16, v50, v16, v50
	v_mul_f32_e32 v16, 0x3f4c422a, v16
	v_mul_f32_e32 v16, 0xc038aa3b, v16
	v_exp_f32_e32 v16, v16
	v_and_b32_e32 v19, 0xffff0000, v19
	v_lshlrev_b32_e32 v22, 16, v23
	v_and_b32_e32 v23, 0xffff0000, v23
	v_add_f32_e32 v16, 1.0, v16
	v_rcp_f32_e32 v52, v16
	v_mul_f32_e32 v16, 0x3d372713, v51
	v_mul_f32_e32 v16, v51, v16
	v_fma_f32 v16, v51, v16, v51
	v_mul_f32_e32 v16, 0x3f4c422a, v16
	v_mul_f32_e32 v16, 0xc038aa3b, v16
	v_exp_f32_e32 v16, v16
	v_mov_b64_e32 v[54:55], v[44:45]
	v_add_f32_e32 v16, 1.0, v16
	v_rcp_f32_e32 v53, v16
	s_nop 0
	v_pk_mul_f32 v[50:51], v[50:51], v[52:53]
	s_nop 0
	v_cvt_pk_bf16_f32 v16, v50, v51
	v_lshlrev_b32_e32 v50, 16, v17
	v_and_b32_e32 v51, 0xffff0000, v17
	v_pk_add_f32 v[18:19], v[50:51], v[18:19]
	s_waitcnt vmcnt(16)
	v_mov_b64_e32 v[50:51], v[34:35]
	v_pk_fma_f32 v[18:19], v[14:15], v[22:23], v[18:19]
	v_mov_b64_e32 v[52:53], v[42:43]
	v_mul_f32_e32 v17, 0x3d372713, v18
	v_mul_f32_e32 v17, v18, v17
	v_fma_f32 v17, v18, v17, v18
	v_mul_f32_e32 v17, 0x3f4c422a, v17
	v_mul_f32_e32 v17, 0xc038aa3b, v17
	v_exp_f32_e32 v17, v17
	s_nop 0
	v_add_f32_e32 v17, 1.0, v17
	v_rcp_f32_e32 v22, v17
	v_mul_f32_e32 v17, 0x3d372713, v19
	v_mul_f32_e32 v17, v19, v17
	v_fma_f32 v17, v19, v17, v19
	v_mul_f32_e32 v17, 0x3f4c422a, v17
	v_mul_f32_e32 v17, 0xc038aa3b, v17
	v_exp_f32_e32 v17, v17
	s_nop 0
	v_add_f32_e32 v17, 1.0, v17
	v_rcp_f32_e32 v23, v17
	s_nop 0
	v_pk_mul_f32 v[18:19], v[18:19], v[22:23]
	s_nop 0
	v_cvt_pk_bf16_f32 v17, v18, v19
	global_store_dwordx2 v[62:63], v[16:17], off offset:1536
	v_mov_b64_e32 v[62:63], v[28:29]
	s_waitcnt vmcnt(16)
	v_mov_b64_e32 v[22:23], v[36:37]
	v_mov_b64_e32 v[16:17], v[46:47]
	v_mov_b64_e32 v[18:19], v[48:49]
	s_andn2_b64 exec, exec, s[12:13]
	s_cbranch_execz .LBB0_329
.LBB0_327:
	v_add_u32_e32 v69, 1, v69
	v_cmp_ge_i32_e64 s[8:9], v69, v106
	v_cmp_lt_i32_e32 vcc, v69, v106
	s_or_b64 s[12:13], s[8:9], s[12:13]
	v_lshl_add_u64 v[70:71], v[20:21], 0, v[180:181]
	s_and_saveexec_b64 s[8:9], vcc
	s_cbranch_execz .LBB0_326
	v_add_co_u32_e32 v26, vcc, 0x17085000, v70
	s_nop 1
	v_addc_co_u32_e32 v27, vcc, 0, v71, vcc
	v_add_co_u32_e32 v28, vcc, 0x1b485000, v70
	s_nop 1
	v_addc_co_u32_e32 v29, vcc, 0, v71, vcc
	v_add_co_u32_e32 v188, vcc, 0x17086000, v70
	v_addc_co_u32_e32 v189, vcc, 0, v71, vcc
	v_add_co_u32_e32 v190, vcc, 0x1b486000, v70
	v_addc_co_u32_e32 v191, vcc, 0, v71, vcc
	global_load_dwordx2 v[32:33], v[26:27], off offset:2048
	global_load_dwordx2 v[38:39], v[26:27], off offset:2560
	global_load_dwordx2 v[44:45], v[26:27], off offset:3072
	global_load_dwordx2 v[48:49], v[26:27], off offset:3584
	s_nop 0
	global_load_dwordx2 v[26:27], v[28:29], off offset:2048
	global_load_dwordx2 v[40:41], v[28:29], off offset:2560
	global_load_dwordx2 v[42:43], v[28:29], off offset:3072
	global_load_dwordx2 v[46:47], v[28:29], off offset:3584
	v_lshl_add_u64 v[28:29], v[24:25], 0, v[180:181]
	v_add_co_u32_e32 v30, vcc, 0x8287000, v28
	s_nop 1
	v_addc_co_u32_e32 v31, vcc, 0, v29, vcc
	v_add_co_u32_e32 v36, vcc, 0x8288000, v28
	s_nop 1
	v_addc_co_u32_e32 v37, vcc, 0, v29, vcc
	v_add_co_u32_e32 v192, vcc, 0x8288c00, v28
	v_addc_co_u32_e32 v193, vcc, 0, v29, vcc
	v_add_co_u32_e32 v194, vcc, 0x8289c00, v28
	v_addc_co_u32_e32 v195, vcc, 0, v29, vcc
	global_load_dwordx2 v[28:29], v[30:31], off
	s_nop 0
	global_load_dwordx2 v[30:31], v[30:31], off offset:3072
	s_nop 0
	global_load_dwordx2 v[34:35], v[36:37], off offset:1024
	s_nop 0
	global_load_dwordx2 v[36:37], v[36:37], off offset:1536
	global_load_dword v196, v[188:189], off
	global_load_dword v196, v[188:189], off offset:512
	global_load_dword v196, v[188:189], off offset:1024
	global_load_dword v196, v[188:189], off offset:1536
	global_load_dword v196, v[190:191], off
	global_load_dword v196, v[190:191], off offset:512
	global_load_dword v196, v[190:191], off offset:1024
	global_load_dword v196, v[190:191], off offset:1536
	global_load_dword v196, v[192:193], off
	global_load_dword v196, v[192:193], off offset:3072
	global_load_dword v196, v[194:195], off offset:1024
	global_load_dword v196, v[194:195], off offset:1536
	s_branch .LBB0_326
